# mirror: one static s_setprio 1 for waves 0-3, all per-segment flips deleted
# baseline (speedup 1.0000x reference)
; #define LAS __attribute__((address_space(3)))
; __global__ void __launch_bounds__(512, 2) fwd_kernel(Args args) {
;     extern __shared__ __attribute__((aligned(16))) unsigned char lds_raw[];
;     LAS unsigned char* lds = (LAS unsigned char*)lds_raw;
;     if (threadIdx.x < 16) ((LAS unsigned*)(lds + 131072))[threadIdx.x] = 0u;
;     __syncthreads();
_Z10fwd_kernel4Args:
	s_load_dwordx2 s[74:75], s[0:1], 0xc8
	v_and_b32_e32 v222, 0x3ff, v0
	s_mov_b64 s[78:79], s[0:1]
	v_cmp_gt_u32_e32 vcc, 16, v222
	s_and_saveexec_b64 s[0:1], vcc
	v_lshl_add_u32 v1, v222, 2, 0
	v_add_u32_e32 v1, 0x20000, v1
	v_mov_b32_e32 v2, 0
	ds_write_b32 v1, v2
	s_or_b64 exec, exec, s[0:1]
	s_waitcnt lgkmcnt(0)
	v_readfirstlane_b32 s98, v222
	s_nop 3
	s_lshr_b32 s98, s98, 8
	s_cmp_eq_u32 s98, 0
	s_cbranch_scc0 .Lprio_done
	s_setprio 1
